# attention loop: older co-resident wave alternates priority 2 (MFMA sections) / 0, younger wave holds a static 1 from phase entry
# speedup vs baseline: 1.0004x; 1.0004x over previous
.LBB0_7:
	s_mov_b32 s38, s42
	s_mov_b32 s0, 0x1fff
	s_bitcmp1_b32 s0, s42
	s_cbranch_scc0 .Lgemm_np
	s_getreg_b32 s0, hwreg(HW_REG_HW_ID, 0, 4)
	s_bitcmp1_b32 s0, 0
	s_cbranch_scc0 .Lgemm_np
	s_setprio 1

.Lattn_ld:
	global_load_dwordx4 v[164:167], v[190:191], off
	global_load_dwordx4 v[148:151], v[190:191], off offset:64
	global_load_dwordx4 v[152:155], v[190:191], off offset:128
	global_load_dwordx4 v[172:175], v[190:191], off offset:192
	global_load_dwordx4 v[156:159], v[242:243], off
	global_load_dwordx4 v[160:163], v[242:243], off offset:64
	v_add_co_u32_e32 v190, vcc, s79, v252
	s_nop 1
	v_addc_co_u32_e32 v191, vcc, 0, v253, vcc
	global_load_dwordx4 v[144:147], v[252:253], off
	global_load_dwordx4 v[168:171], v[190:191], off
	v_add_co_u32_e32 v190, vcc, 0x100000, v252
	s_nop 1
	v_addc_co_u32_e32 v191, vcc, 0, v253, vcc
	v_add_co_u32_e32 v242, vcc, 0x180000, v252
	s_nop 1
	v_addc_co_u32_e32 v243, vcc, 0, v253, vcc
	global_load_dwordx4 v[176:179], v[190:191], off
	global_load_dwordx4 v[180:183], v[242:243], off
	s_cmp_le_i32 s15, s17
	s_cbranch_scc0 .LBB0_57
	s_getreg_b32 s4, hwreg(HW_REG_HW_ID, 0, 4)
	s_bitcmp1_b32 s4, 0
	s_cbranch_scc1 .Lar0
	s_setprio 2
.Lar0:
	s_waitcnt lgkmcnt(7)
	v_mfma_f32_32x32x16_bf16 v[80:95], v[244:247], v[96:99], 0
	ds_read_b128 v[244:247], v220 offset:256
	s_waitcnt lgkmcnt(7)
	v_mfma_f32_32x32x16_bf16 v[80:95], v[248:251], v[100:103], v[80:95]
	ds_read_b128 v[248:251], v220 offset:288
	s_waitcnt lgkmcnt(7)
	v_mfma_f32_32x32x16_bf16 v[80:95], v[222:225], v[104:107], v[80:95]
	ds_read_b128 v[222:225], v220 offset:320
	s_waitcnt lgkmcnt(7)
	v_mfma_f32_32x32x16_bf16 v[80:95], v[230:233], v[108:111], v[80:95]
	ds_read_b128 v[230:233], v220 offset:352
	s_waitcnt lgkmcnt(7)
	v_mfma_f32_32x32x16_bf16 v[80:95], v[64:67], v[112:115], v[80:95]
	s_waitcnt lgkmcnt(6)
	v_mfma_f32_32x32x16_bf16 v[80:95], v[68:71], v[116:119], v[80:95]
	s_waitcnt lgkmcnt(5)
	v_mfma_f32_32x32x16_bf16 v[80:95], v[72:75], v[120:123], v[80:95]
	s_waitcnt lgkmcnt(4)
	v_mfma_f32_32x32x16_bf16 v[80:95], v[76:79], v[124:127], v[80:95]
	s_waitcnt lgkmcnt(3)
	v_mfma_f32_32x32x16_bf16 v[80:95], v[244:247], v[128:131], v[80:95]
	ds_read_b128 v[244:247], v220 offset:12800
	s_waitcnt lgkmcnt(3)
	v_mfma_f32_32x32x16_bf16 v[80:95], v[248:251], v[132:135], v[80:95]
	ds_read_b128 v[248:251], v220 offset:12832
	s_waitcnt lgkmcnt(3)
	v_mfma_f32_32x32x16_bf16 v[80:95], v[222:225], v[136:139], v[80:95]
	ds_read_b128 v[222:225], v220 offset:12864
	s_waitcnt lgkmcnt(3)
	v_mfma_f32_32x32x16_bf16 v[80:95], v[230:233], v[140:143], v[80:95]
	ds_read_b128 v[230:233], v220 offset:12896
	s_waitcnt lgkmcnt(3)
	v_mfma_f32_32x32x16_bf16 v[64:79], v[244:247], v[96:99], 0
	ds_read_b128 v[244:247], v220 offset:12928
	s_waitcnt lgkmcnt(3)
	v_mfma_f32_32x32x16_bf16 v[64:79], v[248:251], v[100:103], v[64:79]
	ds_read_b128 v[248:251], v220 offset:12960
	s_waitcnt lgkmcnt(3)
	v_mfma_f32_32x32x16_bf16 v[64:79], v[222:225], v[104:107], v[64:79]
	ds_read_b128 v[222:225], v220 offset:12992
	s_waitcnt lgkmcnt(3)
	v_mfma_f32_32x32x16_bf16 v[64:79], v[230:233], v[108:111], v[64:79]
	ds_read_b128 v[230:233], v220 offset:13024
	s_waitcnt lgkmcnt(3)
	v_mfma_f32_32x32x16_bf16 v[64:79], v[244:247], v[112:115], v[64:79]
	ds_read_b128 v[244:247], v220 offset:13056
	s_waitcnt lgkmcnt(3)
	v_mfma_f32_32x32x16_bf16 v[64:79], v[248:251], v[116:119], v[64:79]
	ds_read_b128 v[248:251], v220 offset:13088
	s_waitcnt lgkmcnt(3)
	v_mfma_f32_32x32x16_bf16 v[64:79], v[222:225], v[120:123], v[64:79]
	ds_read_b128 v[222:225], v220 offset:13120
	s_waitcnt lgkmcnt(3)
	v_mfma_f32_32x32x16_bf16 v[64:79], v[230:233], v[124:127], v[64:79]
	ds_read_b128 v[230:233], v220 offset:13152
	s_waitcnt lgkmcnt(3)
	v_mfma_f32_32x32x16_bf16 v[64:79], v[244:247], v[128:131], v[64:79]
	s_waitcnt lgkmcnt(2)
	v_mfma_f32_32x32x16_bf16 v[64:79], v[248:251], v[132:135], v[64:79]
	s_waitcnt lgkmcnt(1)
	v_mfma_f32_32x32x16_bf16 v[64:79], v[222:225], v[136:139], v[64:79]
	s_waitcnt lgkmcnt(0)
	v_mfma_f32_32x32x16_bf16 v[64:79], v[230:233], v[140:143], v[64:79]
	s_getreg_b32 s4, hwreg(HW_REG_HW_ID, 0, 4)
	s_bitcmp1_b32 s4, 0
	s_cbranch_scc1 .Lprio_keep0
	s_setprio 0

.Lattn_noresc:
	v_sub_f32_e32 v80, v80, v241
	v_sub_f32_e32 v81, v81, v241
	v_sub_f32_e32 v82, v82, v241
	v_sub_f32_e32 v83, v83, v241
	v_sub_f32_e32 v84, v84, v241
	v_sub_f32_e32 v85, v85, v241
	v_sub_f32_e32 v86, v86, v241
	v_sub_f32_e32 v87, v87, v241
	v_sub_f32_e32 v88, v88, v241
	v_sub_f32_e32 v89, v89, v241
	v_sub_f32_e32 v90, v90, v241
	v_sub_f32_e32 v91, v91, v241
	v_sub_f32_e32 v92, v92, v241
	v_sub_f32_e32 v93, v93, v241
	v_sub_f32_e32 v94, v94, v241
	v_sub_f32_e32 v95, v95, v241
	v_sub_f32_e32 v64, v64, v241
	v_sub_f32_e32 v65, v65, v241
	v_sub_f32_e32 v66, v66, v241
	v_sub_f32_e32 v67, v67, v241
	v_sub_f32_e32 v68, v68, v241
	v_sub_f32_e32 v69, v69, v241
	v_sub_f32_e32 v70, v70, v241
	v_sub_f32_e32 v71, v71, v241
	v_sub_f32_e32 v72, v72, v241
	v_sub_f32_e32 v73, v73, v241
	v_sub_f32_e32 v74, v74, v241
	v_sub_f32_e32 v75, v75, v241
	v_sub_f32_e32 v76, v76, v241
	v_sub_f32_e32 v77, v77, v241
	v_sub_f32_e32 v78, v78, v241
	v_sub_f32_e32 v79, v79, v241
	v_exp_f32_e32 v80, v80
	v_exp_f32_e32 v81, v81
	v_exp_f32_e32 v82, v82
	v_add_f32_e32 v221, v80, v81
	v_exp_f32_e32 v83, v83
	v_add_f32_e32 v221, v221, v82
	v_exp_f32_e32 v84, v84
	v_add_f32_e32 v221, v221, v83
	v_exp_f32_e32 v85, v85
	v_add_f32_e32 v221, v221, v84
	v_exp_f32_e32 v86, v86
	v_add_f32_e32 v221, v221, v85
	v_exp_f32_e32 v87, v87
	v_add_f32_e32 v221, v221, v86
	v_exp_f32_e32 v88, v88
	v_add_f32_e32 v221, v221, v87
	v_exp_f32_e32 v89, v89
	v_add_f32_e32 v221, v221, v88
	v_exp_f32_e32 v90, v90
	v_add_f32_e32 v221, v221, v89
	v_exp_f32_e32 v91, v91
	v_add_f32_e32 v221, v221, v90
	v_exp_f32_e32 v92, v92
	v_add_f32_e32 v221, v221, v91
	v_exp_f32_e32 v93, v93
	v_add_f32_e32 v221, v221, v92
	v_exp_f32_e32 v94, v94
	v_add_f32_e32 v221, v221, v93
	v_exp_f32_e32 v95, v95
	v_add_f32_e32 v221, v221, v94
	v_exp_f32_e32 v64, v64
	v_add_f32_e32 v221, v221, v95
	v_exp_f32_e32 v65, v65
	v_add_f32_e32 v221, v221, v64
	v_exp_f32_e32 v66, v66
	v_add_f32_e32 v221, v221, v65
	v_exp_f32_e32 v67, v67
	v_add_f32_e32 v221, v221, v66
	v_exp_f32_e32 v68, v68
	v_add_f32_e32 v221, v221, v67
	v_exp_f32_e32 v69, v69
	v_add_f32_e32 v221, v221, v68
	v_exp_f32_e32 v70, v70
	v_add_f32_e32 v221, v221, v69
	v_exp_f32_e32 v71, v71
	v_add_f32_e32 v221, v221, v70
	v_exp_f32_e32 v72, v72
	v_add_f32_e32 v221, v221, v71
	v_exp_f32_e32 v73, v73
	v_add_f32_e32 v221, v221, v72
	v_exp_f32_e32 v74, v74
	v_add_f32_e32 v221, v221, v73
	v_exp_f32_e32 v75, v75
	v_add_f32_e32 v221, v221, v74
	v_exp_f32_e32 v76, v76
	v_add_f32_e32 v221, v221, v75
	v_exp_f32_e32 v77, v77
	v_add_f32_e32 v221, v221, v76
	v_exp_f32_e32 v78, v78
	v_add_f32_e32 v221, v221, v77
	v_exp_f32_e32 v79, v79
	v_add_f32_e32 v221, v221, v78
	s_nop 0
	v_add_f32_e32 v221, v221, v79
	v_fmac_f32_e32 v221, v215, v220
	v_cvt_pk_bf16_f32 v80, v80, v81
	v_cvt_pk_bf16_f32 v81, v82, v83
	v_cvt_pk_bf16_f32 v82, v84, v85
	v_cvt_pk_bf16_f32 v83, v86, v87
	v_cvt_pk_bf16_f32 v88, v88, v89
	v_cvt_pk_bf16_f32 v89, v90, v91
	v_cvt_pk_bf16_f32 v90, v92, v93
	v_cvt_pk_bf16_f32 v91, v94, v95
	v_cvt_pk_bf16_f32 v64, v64, v65
	v_cvt_pk_bf16_f32 v65, v66, v67
	v_cvt_pk_bf16_f32 v66, v68, v69
	v_cvt_pk_bf16_f32 v67, v70, v71
	v_cvt_pk_bf16_f32 v72, v72, v73
	v_cvt_pk_bf16_f32 v73, v74, v75
	v_cvt_pk_bf16_f32 v74, v76, v77
	v_cvt_pk_bf16_f32 v75, v78, v79
	v_mov_b32_e32 v215, v221
	v_mov_b32_e32 v240, v241
	ds_read_b128 v[84:87], v239 offset:25632
	ds_read_b128 v[92:95], v239 offset:30240
	ds_read_b128 v[68:71], v239 offset:34848
	ds_read_b128 v[76:79], v239 offset:39456
	s_getreg_b32 s4, hwreg(HW_REG_HW_ID, 0, 4)
	s_bitcmp1_b32 s4, 0
	s_cbranch_scc1 .Lar1
	s_setprio 2
.Lar1:
	s_waitcnt lgkmcnt(7)
	v_mfma_f32_32x32x16_bf16 v[48:63], v[244:247], v[80:83], v[48:63]
	ds_read_b128 v[244:247], v239 offset:25664
	s_waitcnt lgkmcnt(7)
	v_mfma_f32_32x32x16_bf16 v[32:47], v[248:251], v[80:83], v[32:47]
	ds_read_b128 v[248:251], v239 offset:30272
	s_waitcnt lgkmcnt(7)
	v_mfma_f32_32x32x16_bf16 v[16:31], v[222:225], v[80:83], v[16:31]
	ds_read_b128 v[222:225], v239 offset:34880
	s_waitcnt lgkmcnt(7)
	v_mfma_f32_32x32x16_bf16 v[0:15], v[230:233], v[80:83], v[0:15]
	ds_read_b128 v[230:233], v239 offset:39488
	s_waitcnt lgkmcnt(7)
	v_mfma_f32_32x32x16_bf16 v[48:63], v[84:87], v[88:91], v[48:63]
	ds_read_b128 v[84:87], v239 offset:25696
	s_waitcnt lgkmcnt(7)
	v_mfma_f32_32x32x16_bf16 v[32:47], v[92:95], v[88:91], v[32:47]
	ds_read_b128 v[92:95], v239 offset:30304
	s_waitcnt lgkmcnt(7)
	v_mfma_f32_32x32x16_bf16 v[16:31], v[68:71], v[88:91], v[16:31]
	ds_read_b128 v[68:71], v239 offset:34912
	s_waitcnt lgkmcnt(7)
	v_mfma_f32_32x32x16_bf16 v[0:15], v[76:79], v[88:91], v[0:15]
	ds_read_b128 v[76:79], v239 offset:39520
	s_waitcnt lgkmcnt(7)
	v_mfma_f32_32x32x16_bf16 v[48:63], v[244:247], v[64:67], v[48:63]
	s_waitcnt lgkmcnt(6)
	v_mfma_f32_32x32x16_bf16 v[32:47], v[248:251], v[64:67], v[32:47]
	s_waitcnt lgkmcnt(5)
	v_mfma_f32_32x32x16_bf16 v[16:31], v[222:225], v[64:67], v[16:31]
	s_waitcnt lgkmcnt(4)
	v_mfma_f32_32x32x16_bf16 v[0:15], v[230:233], v[64:67], v[0:15]
	s_waitcnt lgkmcnt(3)
	v_mfma_f32_32x32x16_bf16 v[48:63], v[84:87], v[72:75], v[48:63]
	s_waitcnt lgkmcnt(2)
	v_mfma_f32_32x32x16_bf16 v[32:47], v[92:95], v[72:75], v[32:47]
	s_waitcnt lgkmcnt(1)
	v_mfma_f32_32x32x16_bf16 v[16:31], v[68:71], v[72:75], v[16:31]
	s_waitcnt lgkmcnt(0)
	v_mfma_f32_32x32x16_bf16 v[0:15], v[76:79], v[72:75], v[0:15]
	s_getreg_b32 s4, hwreg(HW_REG_HW_ID, 0, 4)
	s_bitcmp1_b32 s4, 0
	s_cbranch_scc1 .Lprio_keep1
	s_setprio 0
